# P3->P4 grid barrier replaced by a 32-workgroup (blockIdx&7) group barrier; the grid-wide completion of P3 is checked at the GroupNorm panel wait
# speedup vs baseline: 1.0145x; 1.0145x over previous
; __device__ __forceinline__ unsigned xb_ld(unsigned* p) { return __hip_atomic_load(p, __ATOMIC_RELAXED, __HIP_MEMORY_SCOPE_AGENT); }
; __device__ __forceinline__ unsigned xb_add(unsigned* p, unsigned v) { return __hip_atomic_fetch_add(p, v, __ATOMIC_RELAXED, __HIP_MEMORY_SCOPE_AGENT); }
; __device__ __forceinline__ void xcd_barrier(const XB& b) {
;     __syncthreads();
;     if (threadIdx.x == 0) {
;         unsigned* bar = b.bar;
;         __builtin_amdgcn_fence(__ATOMIC_RELEASE, "agent");
;         asm volatile("s_waitcnt vmcnt(0)" ::: "memory");
;         const unsigned old = xb_add(&bar[XB_XSUB(b.x)], 1u);
;         const unsigned gen = old / b.nloc;
;         if (old + 1u == (gen + 1u) * b.nloc) {
;             const unsigned og = xb_add(&bar[XB_TOP], 1u);
;             const unsigned target = (og / b.nx + 1u) * b.nx;
;             if (og + 1u != target) while (xb_ld(&bar[XB_TOP]) < target) __builtin_amdgcn_s_sleep(1);
;             xb_add(&bar[XB_XGEN(b.x)], 1u);
;         } else {
;             while (xb_ld(&bar[XB_XGEN(b.x)]) == gen) __builtin_amdgcn_s_sleep(1);
;         }
;         __builtin_amdgcn_fence(__ATOMIC_ACQUIRE, "agent");
;         asm volatile("s_waitcnt vmcnt(0)" ::: "memory");
;     }
;     __syncthreads();
.Linvw_3:
	s_mov_b64 s[0:1], exec
	v_readlane_b32 s4, v253, 2
	v_readlane_b32 s5, v253, 3
	s_and_b64 s[4:5], s[0:1], s[4:5]
	s_mov_b64 exec, s[4:5]
	s_cbranch_execz .LBB0_382
	s_cmpk_lg_i32 s33, 0x100
	s_cbranch_scc1 .Lps_g_orig
	v_mov_b32_e32 v4, 0x1b719c0
	v_mov_b32_e32 v5, 1
	global_atomic_add v4, v5, s[82:83]
	s_and_b32 s97, s2, 7
	s_lshl_b32 s97, s97, 6
	s_add_i32 s97, s97, 0x1b6e908
	v_mov_b32_e32 v4, s97
	global_atomic_add v4, v5, s[82:83]
.Lps_g_poll:
	global_load_dword v6, v4, s[82:83] sc1
	s_waitcnt vmcnt(0)
	v_readfirstlane_b32 s97, v6
	s_cmp_lt_u32 s97, 32
	s_cbranch_scc0 .LBB0_382
	s_sleep 1
	s_branch .Lps_g_poll
.Lps_g_orig:
	s_mov_b64 s[6:7], exec
	s_nop 0
	s_waitcnt vmcnt(0)
	s_waitcnt vmcnt(0)
	s_lshl_b32 s3, s89, 8
	v_readlane_b32 s4, v253, 0
	v_mbcnt_lo_u32_b32 v0, s6, 0
	v_readlane_b32 s5, v253, 1
	s_add_u32 s4, s4, s3
	v_mbcnt_hi_u32_b32 v0, s7, v0
	s_addc_u32 s5, s5, 0
	v_cmp_eq_u32_e32 vcc, 0, v0
	s_and_saveexec_b64 s[8:9], vcc
	s_cbranch_execz .LBB0_366
	s_bcnt1_i32_b64 s3, s[6:7]
	v_mov_b32_e32 v1, 0x1000
	v_mov_b32_e32 v2, s3
	global_atomic_add v1, v1, v2, s[4:5] sc0

; __global__ void __launch_bounds__(512, 2) hymba_fwd(Params p) {
;     ...
;         { pg8::Unit u0; for (int i = 0; S.next(i, u0); ++i) groupnorm_rows(p, u0.pm * 256, u0.pm * 256 + 256); }
;         asm volatile("s_waitcnt vmcnt(0)" ::: "memory");
;         __syncthreads();
.LBB0_400:
	s_waitcnt vmcnt(0)
	s_waitcnt vmcnt(3)
	v_mov_b32_e32 v8, v132
	v_cndmask_b32_e64 v0, 0, 1, s[76:77]
	s_waitcnt lgkmcnt(0)
	s_barrier
	s_cmpk_lg_i32 s33, 0x100
	s_cbranch_scc1 .Lgn_nosync
	v_cmp_eq_u32_e32 vcc, 0, v132
	s_and_saveexec_b64 s[100:101], vcc
	s_cbranch_execz .Lgn_sync_end
	s_lshl_b32 s97, s20, 7
	s_add_i32 s97, s97, 0x7d00000
	v_mov_b32_e32 v2, s97
	v_mov_b32_e32 v3, 1
	s_waitcnt vmcnt(0)
	global_atomic_add v2, v3, s[82:83]
	v_mov_b32_e32 v4, 0x1b71a80
	global_atomic_add v4, v3, s[82:83]
	v_mov_b32_e32 v5, 0x1b719c0
.Lgn_poll:
	s_sleep 1
	global_load_dword v4, v2, s[82:83] sc1
	global_load_dword v6, v5, s[82:83] sc1
	s_waitcnt vmcnt(0)
	v_readfirstlane_b32 s97, v4
	v_readfirstlane_b32 s99, v6
	s_cmp_lt_u32 s97, 4
	s_cbranch_scc1 .Lgn_poll
	s_cmpk_lt_u32 s99, 0x100
	s_cbranch_scc1 .Lgn_poll
